# L1 in-projection epilogue: exact wait counts on the V-tile path so the row-scale wait does not drain the transposed stores
# baseline (speedup 1.0000x reference)
; DI unsigned pk2(float lo, float hi) { f32x2 v = {lo, hi}; bf16x2_t b = __builtin_convertvector(v, bf16x2_t); return __builtin_bit_cast(unsigned, b); }
; DI float rs_from_ss(u64 ssq) { return rsqrtf((float)ssq * (1.f / (1048576.f * 1024.f)) + EPS); }
;     DI void operator()(const AccT& acc, const Unit& u, int wr, int wc, int fr, int fq) const {
;     ...
;             for (int m = 0; m < 4; ++m) { const int row = row0 + ai * 128 + m * 16;
;                 const float s = rs_from_ss(((const u64*)sc)[row]);
;                 bf16_t* rowp = O + (size_t)row * 2048 + col0;
; #pragma unroll
;                 for (int bj = 0; bj < 2; ++bj) { const f32x4 v0 = acc[ai][bj][m][0] * s, v1 = acc[ai][bj][m][1] * s;
;                     u32x4 w; w.x = pk2(v0[0], v0[1]); w.y = pk2(v0[2], v0[3]); w.z = pk2(v1[0], v1[1]); w.w = pk2(v1[2], v1[3]);
;                     *(u32x4*)(rowp + bj * 128) = w;
;                     if (u.pn >= 6) { bf16_t* kt = KT + (size_t)(col0 + bj * 128 - 1536) * S + row;
;                         kt[0] = (bf16_t)(w.x & 0xffffu); kt[(size_t)S] = (bf16_t)(w.x >> 16); kt[(size_t)2 * S] = (bf16_t)(w.y & 0xffffu); kt[(size_t)3 * S] = (bf16_t)(w.y >> 16);
;                         kt[(size_t)4 * S] = (bf16_t)(w.z & 0xffffu); kt[(size_t)5 * S] = (bf16_t)(w.z >> 16); kt[(size_t)6 * S] = (bf16_t)(w.w & 0xffffu); kt[(size_t)7 * S] = (bf16_t)(w.w >> 16); } } }
.LBB0_1310:
	s_nop 0
	v_or_b32_e32 v112, 16, v144
	v_ashrrev_i32_e32 v113, 31, v112
	v_lshl_add_u64 v[114:115], v[112:113], 3, s[4:5]
	s_nop 1
	v_lshlrev_b64 v[112:113], 12, v[112:113]
	v_lshl_add_u64 v[112:113], s[2:3], 0, v[112:113]
	v_lshl_add_u64 v[112:113], v[152:153], 1, v[112:113]
	s_cmp_lg_u64 s[8:9], 0
	s_cbranch_scc1 .Lvw1n
	s_waitcnt vmcnt(24)
	s_branch .Lvw1d
.Lvw1n:
	s_waitcnt vmcnt(8)
.Lvw1d:
	v_ffbh_u32_e32 v118, v203
	v_min_u32_e32 v118, 32, v118
	v_lshlrev_b64 v[114:115], v118, v[202:203]
	v_min_u32_e32 v114, 1, v114
	v_or_b32_e32 v114, v115, v114
	v_cvt_f32_u32_e32 v114, v114
	v_sub_u32_e32 v115, 32, v118
	v_ldexp_f32 v114, v114, v115
	v_fmamk_f32 v114, v114, 0x30800000, v162
	v_mul_f32_e32 v115, 0x4b800000, v114
	v_cmp_gt_f32_e32 vcc, s63, v114
	s_nop 1
	v_cndmask_b32_e32 v114, v114, v115, vcc
	v_rsq_f32_e32 v114, v114
	s_nop 0
	v_mul_f32_e32 v115, 0x45800000, v114
	v_cndmask_b32_e32 v114, v114, v115, vcc
	v_pk_mul_f32 v[110:111], v[110:111], v[114:115] op_sel_hi:[1,0]
	v_pk_mul_f32 v[108:109], v[108:109], v[114:115] op_sel_hi:[1,0]
	v_pk_mul_f32 v[118:119], v[106:107], v[114:115] op_sel_hi:[1,0]
	v_pk_mul_f32 v[106:107], v[104:105], v[114:115] op_sel_hi:[1,0]
	v_cvt_pk_bf16_f32 v104, v108, v109
	v_cvt_pk_bf16_f32 v105, v110, v111
	v_cvt_pk_bf16_f32 v106, v106, v107
	v_cvt_pk_bf16_f32 v107, v118, v119
	s_and_b64 vcc, exec, s[8:9]
	global_store_dwordx4 v[112:113], v[104:107], off
	s_cbranch_vccnz .LBB0_1312
	v_lshlrev_b64 v[108:109], 15, v[148:149]
	v_lshl_add_u64 v[108:109], s[12:13], 0, v[108:109]
	v_lshl_add_u64 v[108:109], v[144:145], 1, v[108:109]
	v_add_co_u32_e32 v110, vcc, 0x8000, v108
	global_store_short v[108:109], v104, off offset:32
	s_nop 0
	v_addc_co_u32_e32 v111, vcc, 0, v109, vcc
	global_store_short_d16_hi v[110:111], v104, off offset:32
	v_add_co_u32_e32 v110, vcc, 0x10000, v108
	s_nop 1
	v_addc_co_u32_e32 v111, vcc, 0, v109, vcc
	global_store_short v[110:111], v105, off offset:32
	v_add_co_u32_e32 v110, vcc, 0x18000, v108
	s_nop 1
	v_addc_co_u32_e32 v111, vcc, 0, v109, vcc
	v_add_co_u32_e32 v104, vcc, 0x20000, v108
	global_store_short_d16_hi v[110:111], v105, off offset:32
	s_nop 0
	v_addc_co_u32_e32 v105, vcc, 0, v109, vcc
	global_store_short v[104:105], v106, off offset:32
	v_add_co_u32_e32 v104, vcc, 0x28000, v108
	s_nop 1
	v_addc_co_u32_e32 v105, vcc, 0, v109, vcc
	global_store_short_d16_hi v[104:105], v106, off offset:32
	v_add_co_u32_e32 v104, vcc, 0x30000, v108
	s_nop 1
	v_addc_co_u32_e32 v105, vcc, 0, v109, vcc
	global_store_short v[104:105], v107, off offset:32
	v_add_co_u32_e32 v104, vcc, 0x38000, v108
	s_nop 1
	v_addc_co_u32_e32 v105, vcc, 0, v109, vcc
	global_store_short_d16_hi v[104:105], v107, off offset:32

; DI unsigned pk2(float lo, float hi) { f32x2 v = {lo, hi}; bf16x2_t b = __builtin_convertvector(v, bf16x2_t); return __builtin_bit_cast(unsigned, b); }
; DI float rs_from_ss(u64 ssq) { return rsqrtf((float)ssq * (1.f / (1048576.f * 1024.f)) + EPS); }
;     DI void operator()(const AccT& acc, const Unit& u, int wr, int wc, int fr, int fq) const {
;     ...
;             for (int m = 0; m < 4; ++m) { const int row = row0 + ai * 128 + m * 16;
;                 const float s = rs_from_ss(((const u64*)sc)[row]);
;                 bf16_t* rowp = O + (size_t)row * 2048 + col0;
; #pragma unroll
;                 for (int bj = 0; bj < 2; ++bj) { const f32x4 v0 = acc[ai][bj][m][0] * s, v1 = acc[ai][bj][m][1] * s;
;                     u32x4 w; w.x = pk2(v0[0], v0[1]); w.y = pk2(v0[2], v0[3]); w.z = pk2(v1[0], v1[1]); w.w = pk2(v1[2], v1[3]);
;                     *(u32x4*)(rowp + bj * 128) = w;
;                     if (u.pn >= 6) { bf16_t* kt = KT + (size_t)(col0 + bj * 128 - 1536) * S + row;
;                         kt[0] = (bf16_t)(w.x & 0xffffu); kt[(size_t)S] = (bf16_t)(w.x >> 16); kt[(size_t)2 * S] = (bf16_t)(w.y & 0xffffu); kt[(size_t)3 * S] = (bf16_t)(w.y >> 16);
;                         kt[(size_t)4 * S] = (bf16_t)(w.z & 0xffffu); kt[(size_t)5 * S] = (bf16_t)(w.z >> 16); kt[(size_t)6 * S] = (bf16_t)(w.w & 0xffffu); kt[(size_t)7 * S] = (bf16_t)(w.w >> 16); } } }
.LBB0_1314:
	s_nop 0
	v_or_b32_e32 v96, 32, v144
	v_ashrrev_i32_e32 v97, 31, v96
	v_lshl_add_u64 v[98:99], v[96:97], 3, s[4:5]
	s_nop 1
	v_lshlrev_b64 v[96:97], 12, v[96:97]
	v_lshl_add_u64 v[96:97], s[2:3], 0, v[96:97]
	v_lshl_add_u64 v[96:97], v[152:153], 1, v[96:97]
	s_cmp_lg_u64 s[8:9], 0
	s_cbranch_scc1 .Lvw2n
	s_waitcnt vmcnt(41)
	s_branch .Lvw2d
.Lvw2n:
	s_waitcnt vmcnt(9)
.Lvw2d:
	v_ffbh_u32_e32 v100, v205
	v_min_u32_e32 v100, 32, v100
	v_lshlrev_b64 v[98:99], v100, v[204:205]
	v_min_u32_e32 v98, 1, v98
	v_or_b32_e32 v98, v99, v98
	v_cvt_f32_u32_e32 v98, v98
	v_sub_u32_e32 v99, 32, v100
	v_ldexp_f32 v98, v98, v99
	v_fmamk_f32 v98, v98, 0x30800000, v162
	v_mul_f32_e32 v99, 0x4b800000, v98
	v_cmp_gt_f32_e32 vcc, s63, v98
	s_nop 1
	v_cndmask_b32_e32 v98, v98, v99, vcc
	v_rsq_f32_e32 v98, v98
	s_nop 0
	v_mul_f32_e32 v99, 0x45800000, v98
	v_cndmask_b32_e32 v98, v98, v99, vcc
	v_pk_mul_f32 v[94:95], v[94:95], v[98:99] op_sel_hi:[1,0]
	v_pk_mul_f32 v[92:93], v[92:93], v[98:99] op_sel_hi:[1,0]
	v_pk_mul_f32 v[100:101], v[90:91], v[98:99] op_sel_hi:[1,0]
	v_pk_mul_f32 v[90:91], v[88:89], v[98:99] op_sel_hi:[1,0]
	v_cvt_pk_bf16_f32 v88, v92, v93
	v_cvt_pk_bf16_f32 v89, v94, v95
	v_cvt_pk_bf16_f32 v90, v90, v91
	v_cvt_pk_bf16_f32 v91, v100, v101
	s_and_b64 vcc, exec, s[8:9]
	global_store_dwordx4 v[96:97], v[88:91], off
	s_cbranch_vccnz .LBB0_1316
	v_lshlrev_b64 v[92:93], 15, v[148:149]
	v_lshl_add_u64 v[92:93], s[12:13], 0, v[92:93]
	v_lshl_add_u64 v[92:93], v[144:145], 1, v[92:93]
	v_add_co_u32_e32 v94, vcc, 0x8000, v92
	global_store_short v[92:93], v88, off offset:64
	s_nop 0
	v_addc_co_u32_e32 v95, vcc, 0, v93, vcc
	global_store_short_d16_hi v[94:95], v88, off offset:64
	v_add_co_u32_e32 v94, vcc, 0x10000, v92
	s_nop 1
	v_addc_co_u32_e32 v95, vcc, 0, v93, vcc
	global_store_short v[94:95], v89, off offset:64
	v_add_co_u32_e32 v94, vcc, 0x18000, v92
	s_nop 1
	v_addc_co_u32_e32 v95, vcc, 0, v93, vcc
	v_add_co_u32_e32 v88, vcc, 0x20000, v92
	global_store_short_d16_hi v[94:95], v89, off offset:64
	s_nop 0
	v_addc_co_u32_e32 v89, vcc, 0, v93, vcc
	global_store_short v[88:89], v90, off offset:64
	v_add_co_u32_e32 v88, vcc, 0x28000, v92
	s_nop 1
	v_addc_co_u32_e32 v89, vcc, 0, v93, vcc
	global_store_short_d16_hi v[88:89], v90, off offset:64
	v_add_co_u32_e32 v88, vcc, 0x30000, v92
	s_nop 1
	v_addc_co_u32_e32 v89, vcc, 0, v93, vcc
	global_store_short v[88:89], v91, off offset:64
	v_add_co_u32_e32 v88, vcc, 0x38000, v92
	s_nop 1
	v_addc_co_u32_e32 v89, vcc, 0, v93, vcc
	global_store_short_d16_hi v[88:89], v91, off offset:64

; DI unsigned pk2(float lo, float hi) { f32x2 v = {lo, hi}; bf16x2_t b = __builtin_convertvector(v, bf16x2_t); return __builtin_bit_cast(unsigned, b); }
; DI float rs_from_ss(u64 ssq) { return rsqrtf((float)ssq * (1.f / (1048576.f * 1024.f)) + EPS); }
;     DI void operator()(const AccT& acc, const Unit& u, int wr, int wc, int fr, int fq) const {
;     ...
;             for (int m = 0; m < 4; ++m) { const int row = row0 + ai * 128 + m * 16;
;                 const float s = rs_from_ss(((const u64*)sc)[row]);
;                 bf16_t* rowp = O + (size_t)row * 2048 + col0;
; #pragma unroll
;                 for (int bj = 0; bj < 2; ++bj) { const f32x4 v0 = acc[ai][bj][m][0] * s, v1 = acc[ai][bj][m][1] * s;
;                     u32x4 w; w.x = pk2(v0[0], v0[1]); w.y = pk2(v0[2], v0[3]); w.z = pk2(v1[0], v1[1]); w.w = pk2(v1[2], v1[3]);
;                     *(u32x4*)(rowp + bj * 128) = w;
;                     if (u.pn >= 6) { bf16_t* kt = KT + (size_t)(col0 + bj * 128 - 1536) * S + row;
;                         kt[0] = (bf16_t)(w.x & 0xffffu); kt[(size_t)S] = (bf16_t)(w.x >> 16); kt[(size_t)2 * S] = (bf16_t)(w.y & 0xffffu); kt[(size_t)3 * S] = (bf16_t)(w.y >> 16);
;                         kt[(size_t)4 * S] = (bf16_t)(w.z & 0xffffu); kt[(size_t)5 * S] = (bf16_t)(w.z >> 16); kt[(size_t)6 * S] = (bf16_t)(w.w & 0xffffu); kt[(size_t)7 * S] = (bf16_t)(w.w >> 16); } } }
.LBB0_1318:
	s_nop 0
	v_or_b32_e32 v80, 48, v144
	v_ashrrev_i32_e32 v81, 31, v80
	v_lshl_add_u64 v[82:83], v[80:81], 3, s[4:5]
	s_nop 1
	v_lshlrev_b64 v[80:81], 12, v[80:81]
	v_lshl_add_u64 v[80:81], s[2:3], 0, v[80:81]
	v_lshl_add_u64 v[80:81], v[152:153], 1, v[80:81]
	s_cmp_lg_u64 s[8:9], 0
	s_cbranch_scc1 .Lvw3n
	s_waitcnt vmcnt(58)
	s_branch .Lvw3d
.Lvw3n:
	s_waitcnt vmcnt(10)
.Lvw3d:
	v_ffbh_u32_e32 v84, v207
	v_min_u32_e32 v84, 32, v84
	v_lshlrev_b64 v[82:83], v84, v[206:207]
	v_min_u32_e32 v82, 1, v82
	v_or_b32_e32 v82, v83, v82
	v_cvt_f32_u32_e32 v82, v82
	v_sub_u32_e32 v83, 32, v84
	v_ldexp_f32 v82, v82, v83
	v_fmamk_f32 v82, v82, 0x30800000, v162
	v_mul_f32_e32 v83, 0x4b800000, v82
	v_cmp_gt_f32_e32 vcc, s63, v82
	s_nop 1
	v_cndmask_b32_e32 v82, v82, v83, vcc
	v_rsq_f32_e32 v82, v82
	s_nop 0
	v_mul_f32_e32 v83, 0x45800000, v82
	v_cndmask_b32_e32 v82, v82, v83, vcc
	v_pk_mul_f32 v[78:79], v[78:79], v[82:83] op_sel_hi:[1,0]
	v_pk_mul_f32 v[76:77], v[76:77], v[82:83] op_sel_hi:[1,0]
	v_pk_mul_f32 v[84:85], v[74:75], v[82:83] op_sel_hi:[1,0]
	v_pk_mul_f32 v[74:75], v[72:73], v[82:83] op_sel_hi:[1,0]
	v_cvt_pk_bf16_f32 v72, v76, v77
	v_cvt_pk_bf16_f32 v73, v78, v79
	v_cvt_pk_bf16_f32 v74, v74, v75
	v_cvt_pk_bf16_f32 v75, v84, v85
	s_and_b64 vcc, exec, s[8:9]
	global_store_dwordx4 v[80:81], v[72:75], off
	s_cbranch_vccnz .LBB0_1320
	v_lshlrev_b64 v[76:77], 15, v[148:149]
	v_lshl_add_u64 v[76:77], s[12:13], 0, v[76:77]
	v_lshl_add_u64 v[76:77], v[144:145], 1, v[76:77]
	v_add_co_u32_e32 v78, vcc, 0x8000, v76
	global_store_short v[76:77], v72, off offset:96
	s_nop 0
	v_addc_co_u32_e32 v79, vcc, 0, v77, vcc
	global_store_short_d16_hi v[78:79], v72, off offset:96
	v_add_co_u32_e32 v78, vcc, 0x10000, v76
	s_nop 1
	v_addc_co_u32_e32 v79, vcc, 0, v77, vcc
	global_store_short v[78:79], v73, off offset:96
	v_add_co_u32_e32 v78, vcc, 0x18000, v76
	s_nop 1
	v_addc_co_u32_e32 v79, vcc, 0, v77, vcc
	v_add_co_u32_e32 v72, vcc, 0x20000, v76
	global_store_short_d16_hi v[78:79], v73, off offset:96
	s_nop 0
	v_addc_co_u32_e32 v73, vcc, 0, v77, vcc
	global_store_short v[72:73], v74, off offset:96
	v_add_co_u32_e32 v72, vcc, 0x28000, v76
	s_nop 1
	v_addc_co_u32_e32 v73, vcc, 0, v77, vcc
	global_store_short_d16_hi v[72:73], v74, off offset:96
	v_add_co_u32_e32 v72, vcc, 0x30000, v76
	s_nop 1
	v_addc_co_u32_e32 v73, vcc, 0, v77, vcc
	global_store_short v[72:73], v75, off offset:96
	v_add_co_u32_e32 v72, vcc, 0x38000, v76
	s_nop 1
	v_addc_co_u32_e32 v73, vcc, 0, v77, vcc
	global_store_short_d16_hi v[72:73], v75, off offset:96

; DI unsigned pk2(float lo, float hi) { f32x2 v = {lo, hi}; bf16x2_t b = __builtin_convertvector(v, bf16x2_t); return __builtin_bit_cast(unsigned, b); }
; DI float rs_from_ss(u64 ssq) { return rsqrtf((float)ssq * (1.f / (1048576.f * 1024.f)) + EPS); }
;     DI void operator()(const AccT& acc, const Unit& u, int wr, int wc, int fr, int fq) const {
;     ...
;             for (int m = 0; m < 4; ++m) { const int row = row0 + ai * 128 + m * 16;
;                 const float s = rs_from_ss(((const u64*)sc)[row]);
;                 bf16_t* rowp = O + (size_t)row * 2048 + col0;
; #pragma unroll
;                 for (int bj = 0; bj < 2; ++bj) { const f32x4 v0 = acc[ai][bj][m][0] * s, v1 = acc[ai][bj][m][1] * s;
;                     u32x4 w; w.x = pk2(v0[0], v0[1]); w.y = pk2(v0[2], v0[3]); w.z = pk2(v1[0], v1[1]); w.w = pk2(v1[2], v1[3]);
;                     *(u32x4*)(rowp + bj * 128) = w;
;                     if (u.pn >= 6) { bf16_t* kt = KT + (size_t)(col0 + bj * 128 - 1536) * S + row;
;                         kt[0] = (bf16_t)(w.x & 0xffffu); kt[(size_t)S] = (bf16_t)(w.x >> 16); kt[(size_t)2 * S] = (bf16_t)(w.y & 0xffffu); kt[(size_t)3 * S] = (bf16_t)(w.y >> 16);
;                         kt[(size_t)4 * S] = (bf16_t)(w.z & 0xffffu); kt[(size_t)5 * S] = (bf16_t)(w.z >> 16); kt[(size_t)6 * S] = (bf16_t)(w.w & 0xffffu); kt[(size_t)7 * S] = (bf16_t)(w.w >> 16); } } }
.LBB0_1322:
	s_nop 1
	s_cmp_lg_u64 s[8:9], 0
	s_cbranch_scc1 .Lvw4n
	s_waitcnt vmcnt(63)
	s_branch .Lvw4d
.Lvw4n:
	s_waitcnt vmcnt(11)
.Lvw4d:
	v_ffbh_u32_e32 v66, v209
	v_min_u32_e32 v67, 32, v66
	v_lshlrev_b64 v[64:65], v67, v[208:209]
	v_min_u32_e32 v64, 1, v64
	v_or_b32_e32 v64, v65, v64
	v_cvt_f32_u32_e32 v64, v64
	v_sub_u32_e32 v65, 32, v67
	v_add_co_u32_e32 v66, vcc, 0x80000, v146
	v_ldexp_f32 v64, v64, v65
	v_fmamk_f32 v64, v64, 0x30800000, v162
	v_mul_f32_e32 v65, 0x4b800000, v64
	v_cmp_gt_f32_e64 s[10:11], s63, v64
	v_addc_co_u32_e32 v67, vcc, 0, v147, vcc
	s_nop 0
	v_cndmask_b32_e64 v64, v64, v65, s[10:11]
	v_rsq_f32_e32 v64, v64
	s_and_b64 vcc, exec, s[8:9]
	v_mul_f32_e32 v65, 0x45800000, v64
	v_cndmask_b32_e64 v64, v64, v65, s[10:11]
	v_pk_mul_f32 v[62:63], v[62:63], v[64:65] op_sel_hi:[1,0]
	v_pk_mul_f32 v[60:61], v[60:61], v[64:65] op_sel_hi:[1,0]
	v_pk_mul_f32 v[68:69], v[58:59], v[64:65] op_sel_hi:[1,0]
	v_pk_mul_f32 v[58:59], v[56:57], v[64:65] op_sel_hi:[1,0]
	v_cvt_pk_bf16_f32 v56, v60, v61
	v_cvt_pk_bf16_f32 v57, v62, v63
	v_cvt_pk_bf16_f32 v58, v58, v59
	v_cvt_pk_bf16_f32 v59, v68, v69
	global_store_dwordx4 v[66:67], v[56:59], off
	s_cbranch_vccnz .LBB0_1324
	v_lshlrev_b64 v[60:61], 15, v[148:149]
	v_lshl_add_u64 v[60:61], s[12:13], 0, v[60:61]
	v_lshl_add_u64 v[60:61], v[144:145], 1, v[60:61]
	v_add_co_u32_e32 v62, vcc, 0x8000, v60
	global_store_short v[60:61], v56, off offset:256
	s_nop 0
	v_addc_co_u32_e32 v63, vcc, 0, v61, vcc
	global_store_short_d16_hi v[62:63], v56, off offset:256
	v_add_co_u32_e32 v62, vcc, 0x10000, v60
	s_nop 1
	v_addc_co_u32_e32 v63, vcc, 0, v61, vcc
	global_store_short v[62:63], v57, off offset:256
	v_add_co_u32_e32 v62, vcc, 0x18000, v60
	s_nop 1
	v_addc_co_u32_e32 v63, vcc, 0, v61, vcc
	v_add_co_u32_e32 v56, vcc, 0x20000, v60
	global_store_short_d16_hi v[62:63], v57, off offset:256
	s_nop 0
	v_addc_co_u32_e32 v57, vcc, 0, v61, vcc
	global_store_short v[56:57], v58, off offset:256
	v_add_co_u32_e32 v56, vcc, 0x28000, v60
	s_nop 1
	v_addc_co_u32_e32 v57, vcc, 0, v61, vcc
	global_store_short_d16_hi v[56:57], v58, off offset:256
	v_add_co_u32_e32 v56, vcc, 0x30000, v60
	s_nop 1
	v_addc_co_u32_e32 v57, vcc, 0, v61, vcc
	global_store_short v[56:57], v59, off offset:256
	v_add_co_u32_e32 v56, vcc, 0x38000, v60
	s_nop 1
	v_addc_co_u32_e32 v57, vcc, 0, v61, vcc
	global_store_short_d16_hi v[56:57], v59, off offset:256

; DI unsigned pk2(float lo, float hi) { f32x2 v = {lo, hi}; bf16x2_t b = __builtin_convertvector(v, bf16x2_t); return __builtin_bit_cast(unsigned, b); }
; DI float rs_from_ss(u64 ssq) { return rsqrtf((float)ssq * (1.f / (1048576.f * 1024.f)) + EPS); }
;     DI void operator()(const AccT& acc, const Unit& u, int wr, int wc, int fr, int fq) const {
;     ...
;             for (int m = 0; m < 4; ++m) { const int row = row0 + ai * 128 + m * 16;
;                 const float s = rs_from_ss(((const u64*)sc)[row]);
;                 bf16_t* rowp = O + (size_t)row * 2048 + col0;
; #pragma unroll
;                 for (int bj = 0; bj < 2; ++bj) { const f32x4 v0 = acc[ai][bj][m][0] * s, v1 = acc[ai][bj][m][1] * s;
;                     u32x4 w; w.x = pk2(v0[0], v0[1]); w.y = pk2(v0[2], v0[3]); w.z = pk2(v1[0], v1[1]); w.w = pk2(v1[2], v1[3]);
;                     *(u32x4*)(rowp + bj * 128) = w;
;                     if (u.pn >= 6) { bf16_t* kt = KT + (size_t)(col0 + bj * 128 - 1536) * S + row;
;                         kt[0] = (bf16_t)(w.x & 0xffffu); kt[(size_t)S] = (bf16_t)(w.x >> 16); kt[(size_t)2 * S] = (bf16_t)(w.y & 0xffffu); kt[(size_t)3 * S] = (bf16_t)(w.y >> 16);
;                         kt[(size_t)4 * S] = (bf16_t)(w.z & 0xffffu); kt[(size_t)5 * S] = (bf16_t)(w.z >> 16); kt[(size_t)6 * S] = (bf16_t)(w.w & 0xffffu); kt[(size_t)7 * S] = (bf16_t)(w.w >> 16); } } }
.Lvw5n:
	s_waitcnt vmcnt(12)
.Lvw5d:
	v_ffbh_u32_e32 v50, v211
	v_min_u32_e32 v51, 32, v50
	v_lshlrev_b64 v[48:49], v51, v[210:211]
	v_min_u32_e32 v48, 1, v48
	v_or_b32_e32 v48, v49, v48
	v_cvt_f32_u32_e32 v48, v48
	v_sub_u32_e32 v49, 32, v51
	v_add_co_u32_e32 v50, vcc, 0x90000, v146
	v_ldexp_f32 v48, v48, v49
	v_fmamk_f32 v48, v48, 0x30800000, v162
	v_mul_f32_e32 v49, 0x4b800000, v48
	v_cmp_gt_f32_e64 s[10:11], s63, v48
	v_addc_co_u32_e32 v51, vcc, 0, v147, vcc
	s_nop 0
	v_cndmask_b32_e64 v48, v48, v49, s[10:11]
	v_rsq_f32_e32 v48, v48
	s_and_b64 vcc, exec, s[8:9]
	v_mul_f32_e32 v49, 0x45800000, v48
	v_cndmask_b32_e64 v48, v48, v49, s[10:11]
	v_pk_mul_f32 v[46:47], v[46:47], v[48:49] op_sel_hi:[1,0]
	v_pk_mul_f32 v[44:45], v[44:45], v[48:49] op_sel_hi:[1,0]
	v_pk_mul_f32 v[52:53], v[42:43], v[48:49] op_sel_hi:[1,0]
	v_pk_mul_f32 v[42:43], v[40:41], v[48:49] op_sel_hi:[1,0]
	v_cvt_pk_bf16_f32 v40, v44, v45
	v_cvt_pk_bf16_f32 v41, v46, v47
	v_cvt_pk_bf16_f32 v42, v42, v43
	v_cvt_pk_bf16_f32 v43, v52, v53
	global_store_dwordx4 v[50:51], v[40:43], off
	s_cbranch_vccnz .LBB0_1328
	v_lshlrev_b64 v[44:45], 15, v[148:149]
	v_lshl_add_u64 v[44:45], s[12:13], 0, v[44:45]
	v_lshl_add_u64 v[44:45], v[144:145], 1, v[44:45]
	v_add_co_u32_e32 v46, vcc, 0x8000, v44
	global_store_short v[44:45], v40, off offset:288
	s_nop 0
	v_addc_co_u32_e32 v47, vcc, 0, v45, vcc
	global_store_short_d16_hi v[46:47], v40, off offset:288
	v_add_co_u32_e32 v46, vcc, 0x10000, v44
	s_nop 1
	v_addc_co_u32_e32 v47, vcc, 0, v45, vcc
	global_store_short v[46:47], v41, off offset:288
	v_add_co_u32_e32 v46, vcc, 0x18000, v44
	s_nop 1
	v_addc_co_u32_e32 v47, vcc, 0, v45, vcc
	v_add_co_u32_e32 v40, vcc, 0x20000, v44
	global_store_short_d16_hi v[46:47], v41, off offset:288
	s_nop 0
	v_addc_co_u32_e32 v41, vcc, 0, v45, vcc
	global_store_short v[40:41], v42, off offset:288
	v_add_co_u32_e32 v40, vcc, 0x28000, v44
	s_nop 1
	v_addc_co_u32_e32 v41, vcc, 0, v45, vcc
	global_store_short_d16_hi v[40:41], v42, off offset:288
	v_add_co_u32_e32 v40, vcc, 0x30000, v44
	s_nop 1
	v_addc_co_u32_e32 v41, vcc, 0, v45, vcc
	global_store_short v[40:41], v43, off offset:288
	v_add_co_u32_e32 v40, vcc, 0x38000, v44
	s_nop 1
	v_addc_co_u32_e32 v41, vcc, 0, v45, vcc
	global_store_short_d16_hi v[40:41], v43, off offset:288

; DI unsigned pk2(float lo, float hi) { f32x2 v = {lo, hi}; bf16x2_t b = __builtin_convertvector(v, bf16x2_t); return __builtin_bit_cast(unsigned, b); }
; DI float rs_from_ss(u64 ssq) { return rsqrtf((float)ssq * (1.f / (1048576.f * 1024.f)) + EPS); }
;     DI void operator()(const AccT& acc, const Unit& u, int wr, int wc, int fr, int fq) const {
;     ...
;             for (int m = 0; m < 4; ++m) { const int row = row0 + ai * 128 + m * 16;
;                 const float s = rs_from_ss(((const u64*)sc)[row]);
;                 bf16_t* rowp = O + (size_t)row * 2048 + col0;
; #pragma unroll
;                 for (int bj = 0; bj < 2; ++bj) { const f32x4 v0 = acc[ai][bj][m][0] * s, v1 = acc[ai][bj][m][1] * s;
;                     u32x4 w; w.x = pk2(v0[0], v0[1]); w.y = pk2(v0[2], v0[3]); w.z = pk2(v1[0], v1[1]); w.w = pk2(v1[2], v1[3]);
;                     *(u32x4*)(rowp + bj * 128) = w;
;                     if (u.pn >= 6) { bf16_t* kt = KT + (size_t)(col0 + bj * 128 - 1536) * S + row;
;                         kt[0] = (bf16_t)(w.x & 0xffffu); kt[(size_t)S] = (bf16_t)(w.x >> 16); kt[(size_t)2 * S] = (bf16_t)(w.y & 0xffffu); kt[(size_t)3 * S] = (bf16_t)(w.y >> 16);
;                         kt[(size_t)4 * S] = (bf16_t)(w.z & 0xffffu); kt[(size_t)5 * S] = (bf16_t)(w.z >> 16); kt[(size_t)6 * S] = (bf16_t)(w.w & 0xffffu); kt[(size_t)7 * S] = (bf16_t)(w.w >> 16); } } }
.Lvw6n:
	s_waitcnt vmcnt(13)
.Lvw6d:
	v_ffbh_u32_e32 v34, v213
	v_min_u32_e32 v35, 32, v34
	v_lshlrev_b64 v[32:33], v35, v[212:213]
	v_min_u32_e32 v32, 1, v32
	v_or_b32_e32 v32, v33, v32
	v_cvt_f32_u32_e32 v32, v32
	v_sub_u32_e32 v33, 32, v35
	v_add_co_u32_e32 v34, vcc, 0xa0000, v146
	v_ldexp_f32 v32, v32, v33
	v_fmamk_f32 v32, v32, 0x30800000, v162
	v_mul_f32_e32 v33, 0x4b800000, v32
	v_cmp_gt_f32_e64 s[10:11], s63, v32
	v_addc_co_u32_e32 v35, vcc, 0, v147, vcc
	s_nop 0
	v_cndmask_b32_e64 v32, v32, v33, s[10:11]
	v_rsq_f32_e32 v32, v32
	s_and_b64 vcc, exec, s[8:9]
	v_mul_f32_e32 v33, 0x45800000, v32
	v_cndmask_b32_e64 v32, v32, v33, s[10:11]
	v_pk_mul_f32 v[30:31], v[30:31], v[32:33] op_sel_hi:[1,0]
	v_pk_mul_f32 v[28:29], v[28:29], v[32:33] op_sel_hi:[1,0]
	v_pk_mul_f32 v[36:37], v[26:27], v[32:33] op_sel_hi:[1,0]
	v_pk_mul_f32 v[26:27], v[24:25], v[32:33] op_sel_hi:[1,0]
	v_cvt_pk_bf16_f32 v24, v28, v29
	v_cvt_pk_bf16_f32 v25, v30, v31
	v_cvt_pk_bf16_f32 v26, v26, v27
	v_cvt_pk_bf16_f32 v27, v36, v37
	global_store_dwordx4 v[34:35], v[24:27], off
	s_cbranch_vccnz .LBB0_1332
	v_lshlrev_b64 v[28:29], 15, v[148:149]
	v_lshl_add_u64 v[28:29], s[12:13], 0, v[28:29]
	v_lshl_add_u64 v[28:29], v[144:145], 1, v[28:29]
	v_add_co_u32_e32 v30, vcc, 0x8000, v28
	global_store_short v[28:29], v24, off offset:320
	s_nop 0
	v_addc_co_u32_e32 v31, vcc, 0, v29, vcc
	global_store_short_d16_hi v[30:31], v24, off offset:320
	v_add_co_u32_e32 v30, vcc, 0x10000, v28
	s_nop 1
	v_addc_co_u32_e32 v31, vcc, 0, v29, vcc
	global_store_short v[30:31], v25, off offset:320
	v_add_co_u32_e32 v30, vcc, 0x18000, v28
	s_nop 1
	v_addc_co_u32_e32 v31, vcc, 0, v29, vcc
	v_add_co_u32_e32 v24, vcc, 0x20000, v28
	global_store_short_d16_hi v[30:31], v25, off offset:320
	s_nop 0
	v_addc_co_u32_e32 v25, vcc, 0, v29, vcc
	global_store_short v[24:25], v26, off offset:320
	v_add_co_u32_e32 v24, vcc, 0x28000, v28
	s_nop 1
	v_addc_co_u32_e32 v25, vcc, 0, v29, vcc
	global_store_short_d16_hi v[24:25], v26, off offset:320
	v_add_co_u32_e32 v24, vcc, 0x30000, v28
	s_nop 1
	v_addc_co_u32_e32 v25, vcc, 0, v29, vcc
	global_store_short v[24:25], v27, off offset:320
	v_add_co_u32_e32 v24, vcc, 0x38000, v28
	s_nop 1
	v_addc_co_u32_e32 v25, vcc, 0, v29, vcc
	global_store_short_d16_hi v[24:25], v27, off offset:320

; DI unsigned pk2(float lo, float hi) { f32x2 v = {lo, hi}; bf16x2_t b = __builtin_convertvector(v, bf16x2_t); return __builtin_bit_cast(unsigned, b); }
; DI float rs_from_ss(u64 ssq) { return rsqrtf((float)ssq * (1.f / (1048576.f * 1024.f)) + EPS); }
;     DI void operator()(const AccT& acc, const Unit& u, int wr, int wc, int fr, int fq) const {
;     ...
;             for (int m = 0; m < 4; ++m) { const int row = row0 + ai * 128 + m * 16;
;                 const float s = rs_from_ss(((const u64*)sc)[row]);
;                 bf16_t* rowp = O + (size_t)row * 2048 + col0;
; #pragma unroll
;                 for (int bj = 0; bj < 2; ++bj) { const f32x4 v0 = acc[ai][bj][m][0] * s, v1 = acc[ai][bj][m][1] * s;
;                     u32x4 w; w.x = pk2(v0[0], v0[1]); w.y = pk2(v0[2], v0[3]); w.z = pk2(v1[0], v1[1]); w.w = pk2(v1[2], v1[3]);
;                     *(u32x4*)(rowp + bj * 128) = w;
;                     if (u.pn >= 6) { bf16_t* kt = KT + (size_t)(col0 + bj * 128 - 1536) * S + row;
;                         kt[0] = (bf16_t)(w.x & 0xffffu); kt[(size_t)S] = (bf16_t)(w.x >> 16); kt[(size_t)2 * S] = (bf16_t)(w.y & 0xffffu); kt[(size_t)3 * S] = (bf16_t)(w.y >> 16);
;                         kt[(size_t)4 * S] = (bf16_t)(w.z & 0xffffu); kt[(size_t)5 * S] = (bf16_t)(w.z >> 16); kt[(size_t)6 * S] = (bf16_t)(w.w & 0xffffu); kt[(size_t)7 * S] = (bf16_t)(w.w >> 16); } } }
.Lvw7n:
	s_waitcnt vmcnt(14)
.Lvw7d:
	v_ffbh_u32_e32 v18, v215
	v_min_u32_e32 v19, 32, v18
	v_lshlrev_b64 v[16:17], v19, v[214:215]
	v_min_u32_e32 v16, 1, v16
	v_or_b32_e32 v16, v17, v16
	v_cvt_f32_u32_e32 v16, v16
	v_sub_u32_e32 v17, 32, v19
	v_add_co_u32_e32 v18, vcc, 0xb0000, v146
	v_ldexp_f32 v16, v16, v17
	v_fmamk_f32 v16, v16, 0x30800000, v162
	v_mul_f32_e32 v17, 0x4b800000, v16
	v_cmp_gt_f32_e64 s[10:11], s63, v16
	v_addc_co_u32_e32 v19, vcc, 0, v147, vcc
	s_nop 0
	v_cndmask_b32_e64 v16, v16, v17, s[10:11]
	v_rsq_f32_e32 v16, v16
	s_and_b64 vcc, exec, s[8:9]
	v_mul_f32_e32 v17, 0x45800000, v16
	v_cndmask_b32_e64 v16, v16, v17, s[10:11]
	v_pk_mul_f32 v[14:15], v[14:15], v[16:17] op_sel_hi:[1,0]
	v_pk_mul_f32 v[12:13], v[12:13], v[16:17] op_sel_hi:[1,0]
	v_pk_mul_f32 v[20:21], v[10:11], v[16:17] op_sel_hi:[1,0]
	v_pk_mul_f32 v[10:11], v[8:9], v[16:17] op_sel_hi:[1,0]
	v_cvt_pk_bf16_f32 v8, v12, v13
	v_cvt_pk_bf16_f32 v9, v14, v15
	v_cvt_pk_bf16_f32 v10, v10, v11
	v_cvt_pk_bf16_f32 v11, v20, v21
	global_store_dwordx4 v[18:19], v[8:11], off
	s_cbranch_vccnz .LBB0_1336
	v_lshlrev_b64 v[12:13], 15, v[148:149]
	v_lshl_add_u64 v[12:13], s[12:13], 0, v[12:13]
	v_lshl_add_u64 v[12:13], v[144:145], 1, v[12:13]
	v_add_co_u32_e32 v14, vcc, 0x8000, v12
	global_store_short v[12:13], v8, off offset:352
	s_nop 0
	v_addc_co_u32_e32 v15, vcc, 0, v13, vcc
	global_store_short_d16_hi v[14:15], v8, off offset:352
	v_add_co_u32_e32 v14, vcc, 0x10000, v12
	s_nop 1
	v_addc_co_u32_e32 v15, vcc, 0, v13, vcc
	global_store_short v[14:15], v9, off offset:352
	v_add_co_u32_e32 v14, vcc, 0x18000, v12
	s_nop 1
	v_addc_co_u32_e32 v15, vcc, 0, v13, vcc
	v_add_co_u32_e32 v8, vcc, 0x20000, v12
	global_store_short_d16_hi v[14:15], v9, off offset:352
	s_nop 0
	v_addc_co_u32_e32 v9, vcc, 0, v13, vcc
	global_store_short v[8:9], v10, off offset:352
	v_add_co_u32_e32 v8, vcc, 0x28000, v12
	s_nop 1
	v_addc_co_u32_e32 v9, vcc, 0, v13, vcc
	global_store_short_d16_hi v[8:9], v10, off offset:352
	v_add_co_u32_e32 v8, vcc, 0x30000, v12
	s_nop 1
	v_addc_co_u32_e32 v9, vcc, 0, v13, vcc
	global_store_short v[8:9], v11, off offset:352
	v_add_co_u32_e32 v8, vcc, 0x38000, v12
	s_nop 1
	v_addc_co_u32_e32 v9, vcc, 0, v13, vcc
	global_store_short_d16_hi v[8:9], v11, off offset:352
